# strategy 7.5: SwiGLU epilogue packed f32 ops split into scalar pairs, OPSEL pads removed (on v044)
# speedup vs baseline: 1.0015x; 1.0011x over previous
; DI unsigned pk2(float lo, float hi) { f32x2 v = {lo, hi}; return __builtin_bit_cast(unsigned, __builtin_convertvector(v, bf2_t)); }
; DI f32x2 swiglu_pk(f32x2 g, f32x2 u) {
;     const f32x2 t = g * (-1.44269504089f);
;     f32x2 e; e.x = __builtin_amdgcn_exp2f(t.x); e.y = __builtin_amdgcn_exp2f(t.y);
;     const f32x2 d = e + 1.0f;
;     f32x2 r; r.x = __builtin_amdgcn_rcpf(d.x); r.y = __builtin_amdgcn_rcpf(d.y);
;     return (g * r) * u;
; }
;     DI void operator()(const f32x4 (&acc)[2][2][4][2], const Unit& u, int wr, int wc, int fr, int fq) const {
;         const int row0 = u.pm * BM + wr * 64 + fr, col0 = u.pn * HALF + wc * 32 + 8 * fq;
; #pragma unroll
;         for (int ai = 0; ai < 2; ++ai)
; #pragma unroll
;             for (int m = 0; m < 4; ++m) {
;                 bf16_t* rowp = H + (size_t)(row0 + ai * HALF + m * 16) * ldh + col0;
;                 const f32x4 g0 = acc[ai][0][m][0], g1 = acc[ai][0][m][1], u0 = acc[ai][1][m][0], u1 = acc[ai][1][m][1];
;                 const f32x2 ha = swiglu_pk((f32x2){g0[0], g0[1]}, (f32x2){u0[0], u0[1]}), hb = swiglu_pk((f32x2){g0[2], g0[3]}, (f32x2){u0[2], u0[3]});
;                 const f32x2 hc = swiglu_pk((f32x2){g1[0], g1[1]}, (f32x2){u1[0], u1[1]}), hd = swiglu_pk((f32x2){g1[2], g1[3]}, (f32x2){u1[2], u1[3]});
;                 u32x4 w; w.x = pk2(ha.x, ha.y); w.y = pk2(hb.x, hb.y); w.z = pk2(hc.x, hc.y); w.w = pk2(hd.x, hd.y);
;                 *(u32x4*)rowp = w;
;             }
.LBB0_243:
	v_mul_f32_e32 v152, s30, v126
	v_mul_f32_e32 v153, s30, v127
	v_lshl_or_b32 v142, s50, 7, v146
	v_exp_f32_e32 v152, v152
	v_exp_f32_e32 v153, v153
	v_lshl_add_u32 v148, s52, 8, v144
	v_ashrrev_i32_e32 v143, 31, v142
	v_mov_b64_e32 v[140:141], s[80:81]
	v_add_f32_e32 v152, 1.0, v152
	v_add_f32_e32 v153, 1.0, v153
	v_mad_i64_i32 v[150:151], s[20:21], v148, s15, v[140:141]
	v_rcp_f32_e32 v152, v152
	v_rcp_f32_e32 v153, v153
	v_lshlrev_b64 v[142:143], 1, v[142:143]
	v_lshl_add_u64 v[150:151], v[150:151], 0, v[142:143]
	s_andn2_b64 vcc, exec, s[40:41]
	v_mul_f32_e32 v126, v126, v152
	v_mul_f32_e32 v127, v127, v153
	v_mul_f32_e32 v122, v126, v122
	v_mul_f32_e32 v123, v127, v123
	v_mul_f32_e32 v126, s30, v128
	v_mul_f32_e32 v127, s30, v129
	v_exp_f32_e32 v126, v126
	v_exp_f32_e32 v127, v127
	v_add_f32_e32 v126, 1.0, v126
	v_add_f32_e32 v127, 1.0, v127
	v_rcp_f32_e32 v126, v126
	v_rcp_f32_e32 v127, v127
	v_mul_f32_e32 v126, v128, v126
	v_mul_f32_e32 v127, v129, v127
	v_mul_f32_e32 v124, v126, v124
	v_mul_f32_e32 v125, v127, v125
	v_mul_f32_e32 v126, s30, v118
	v_mul_f32_e32 v127, s30, v119
	v_exp_f32_e32 v126, v126
	v_exp_f32_e32 v127, v127
	v_add_f32_e32 v126, 1.0, v126
	v_add_f32_e32 v127, 1.0, v127
	v_rcp_f32_e32 v126, v126
	v_rcp_f32_e32 v127, v127
	v_mul_f32_e32 v118, v118, v126
	v_mul_f32_e32 v119, v119, v127
	v_mul_f32_e32 v118, v118, v114
	v_mul_f32_e32 v119, v119, v115
	v_mul_f32_e32 v114, s30, v120
	v_mul_f32_e32 v115, s30, v121
	v_exp_f32_e32 v114, v114
	v_exp_f32_e32 v115, v115
	v_add_f32_e32 v114, 1.0, v114
	v_add_f32_e32 v115, 1.0, v115
	v_rcp_f32_e32 v114, v114
	v_rcp_f32_e32 v115, v115
	v_mul_f32_e32 v114, v120, v114
	v_mul_f32_e32 v115, v121, v115
	v_mul_f32_e32 v120, v114, v116
	v_mul_f32_e32 v121, v115, v117
	v_cvt_pk_bf16_f32 v114, v122, v123
	v_cvt_pk_bf16_f32 v115, v124, v125
	v_cvt_pk_bf16_f32 v116, v118, v119
	v_cvt_pk_bf16_f32 v117, v120, v121
	global_store_dwordx4 v[150:151], v[114:117], off sc1
	s_nop 1
	v_mul_f32_e32 v116, s30, v110
	v_mul_f32_e32 v117, s30, v111
	v_or_b32_e32 v114, 16, v148
	v_exp_f32_e32 v116, v116
	v_exp_f32_e32 v117, v117
	v_mad_i64_i32 v[114:115], s[20:21], v114, s15, v[140:141]
	v_lshl_add_u64 v[114:115], v[114:115], 0, v[142:143]
	v_add_f32_e32 v116, 1.0, v116
	v_add_f32_e32 v117, 1.0, v117
	v_rcp_f32_e32 v116, v116
	v_rcp_f32_e32 v117, v117
	v_mul_f32_e32 v110, v110, v116
	v_mul_f32_e32 v111, v111, v117
	v_mul_f32_e32 v106, v110, v106
	v_mul_f32_e32 v107, v111, v107
	v_mul_f32_e32 v110, s30, v112
	v_mul_f32_e32 v111, s30, v113
	v_exp_f32_e32 v110, v110
	v_exp_f32_e32 v111, v111
	v_add_f32_e32 v110, 1.0, v110
	v_add_f32_e32 v111, 1.0, v111
	v_rcp_f32_e32 v110, v110
	v_rcp_f32_e32 v111, v111
	v_mul_f32_e32 v110, v112, v110
	v_mul_f32_e32 v111, v113, v111
	v_mul_f32_e32 v108, v110, v108
	v_mul_f32_e32 v109, v111, v109
	v_mul_f32_e32 v110, s30, v102
	v_mul_f32_e32 v111, s30, v103
	v_exp_f32_e32 v110, v110
	v_exp_f32_e32 v111, v111
	v_add_f32_e32 v110, 1.0, v110
	v_add_f32_e32 v111, 1.0, v111
	v_rcp_f32_e32 v110, v110
	v_rcp_f32_e32 v111, v111
	v_mul_f32_e32 v102, v102, v110
	v_mul_f32_e32 v103, v103, v111
	v_mul_f32_e32 v102, v102, v98
	v_mul_f32_e32 v103, v103, v99
	v_mul_f32_e32 v98, s30, v104
	v_mul_f32_e32 v99, s30, v105
	v_exp_f32_e32 v98, v98
	v_exp_f32_e32 v99, v99
	v_add_f32_e32 v98, 1.0, v98
	v_add_f32_e32 v99, 1.0, v99
	v_rcp_f32_e32 v98, v98
	v_rcp_f32_e32 v99, v99
	v_mul_f32_e32 v98, v104, v98
	v_mul_f32_e32 v99, v105, v99
	v_mul_f32_e32 v104, v98, v100
	v_mul_f32_e32 v105, v99, v101
	v_cvt_pk_bf16_f32 v98, v106, v107
	v_cvt_pk_bf16_f32 v99, v108, v109
	v_cvt_pk_bf16_f32 v100, v102, v103
	v_cvt_pk_bf16_f32 v101, v104, v105
	global_store_dwordx4 v[114:115], v[98:101], off sc1
	s_nop 1
	v_mul_f32_e32 v100, s30, v92
	v_mul_f32_e32 v101, s30, v93
	v_or_b32_e32 v98, 32, v148
	v_exp_f32_e32 v100, v100
	v_exp_f32_e32 v101, v101
	v_mad_i64_i32 v[98:99], s[20:21], v98, s15, v[140:141]
	v_lshl_add_u64 v[98:99], v[98:99], 0, v[142:143]
	v_add_f32_e32 v100, 1.0, v100
	v_add_f32_e32 v101, 1.0, v101
	v_rcp_f32_e32 v100, v100
	v_rcp_f32_e32 v101, v101
	v_mul_f32_e32 v92, v92, v100
	v_mul_f32_e32 v93, v93, v101
	v_mul_f32_e32 v88, v92, v88
	v_mul_f32_e32 v89, v93, v89
	v_mul_f32_e32 v92, s30, v94
	v_mul_f32_e32 v93, s30, v95
	v_exp_f32_e32 v92, v92
	v_exp_f32_e32 v93, v93
	v_add_f32_e32 v92, 1.0, v92
	v_add_f32_e32 v93, 1.0, v93
	v_rcp_f32_e32 v92, v92
	v_rcp_f32_e32 v93, v93
	v_mul_f32_e32 v92, v94, v92
	v_mul_f32_e32 v93, v95, v93
	v_mul_f32_e32 v90, v92, v90
	v_mul_f32_e32 v91, v93, v91
	v_mul_f32_e32 v92, s30, v84
	v_mul_f32_e32 v93, s30, v85
	v_exp_f32_e32 v92, v92
	v_exp_f32_e32 v93, v93
	v_add_f32_e32 v92, 1.0, v92
	v_add_f32_e32 v93, 1.0, v93
	v_rcp_f32_e32 v92, v92
	v_rcp_f32_e32 v93, v93
	v_mul_f32_e32 v84, v84, v92
	v_mul_f32_e32 v85, v85, v93
	v_mul_f32_e32 v84, v84, v80
	v_mul_f32_e32 v85, v85, v81
	v_mul_f32_e32 v80, s30, v86
	v_mul_f32_e32 v81, s30, v87
	v_exp_f32_e32 v80, v80
	v_exp_f32_e32 v81, v81
	v_add_f32_e32 v80, 1.0, v80
	v_add_f32_e32 v81, 1.0, v81
	v_rcp_f32_e32 v80, v80
	v_rcp_f32_e32 v81, v81
	v_mul_f32_e32 v80, v86, v80
	v_mul_f32_e32 v81, v87, v81
	v_mul_f32_e32 v86, v80, v82
	v_mul_f32_e32 v87, v81, v83
	v_cvt_pk_bf16_f32 v80, v88, v89
	v_cvt_pk_bf16_f32 v81, v90, v91
	v_cvt_pk_bf16_f32 v82, v84, v85
	v_cvt_pk_bf16_f32 v83, v86, v87
	global_store_dwordx4 v[98:99], v[80:83], off sc1
	s_nop 1
	v_mul_f32_e32 v82, s30, v76
	v_mul_f32_e32 v83, s30, v77
	v_or_b32_e32 v80, 48, v148
	v_exp_f32_e32 v82, v82
	v_exp_f32_e32 v83, v83
	v_mad_i64_i32 v[80:81], s[20:21], v80, s15, v[140:141]
	v_lshl_add_u64 v[80:81], v[80:81], 0, v[142:143]
	v_add_f32_e32 v82, 1.0, v82
; DI unsigned pk2(float lo, float hi) { f32x2 v = {lo, hi}; return __builtin_bit_cast(unsigned, __builtin_convertvector(v, bf2_t)); }
; DI f32x2 swiglu_pk(f32x2 g, f32x2 u) {
;     const f32x2 t = g * (-1.44269504089f);
;     f32x2 e; e.x = __builtin_amdgcn_exp2f(t.x); e.y = __builtin_amdgcn_exp2f(t.y);
;     const f32x2 d = e + 1.0f;
;     f32x2 r; r.x = __builtin_amdgcn_rcpf(d.x); r.y = __builtin_amdgcn_rcpf(d.y);
;     return (g * r) * u;
; }
;     DI void operator()(const f32x4 (&acc)[2][2][4][2], const Unit& u, int wr, int wc, int fr, int fq) const {
;         const int row0 = u.pm * BM + wr * 64 + fr, col0 = u.pn * HALF + wc * 32 + 8 * fq;
; #pragma unroll
;         for (int ai = 0; ai < 2; ++ai)
; #pragma unroll
;             for (int m = 0; m < 4; ++m) {
;                 bf16_t* rowp = H + (size_t)(row0 + ai * HALF + m * 16) * ldh + col0;
;                 const f32x4 g0 = acc[ai][0][m][0], g1 = acc[ai][0][m][1], u0 = acc[ai][1][m][0], u1 = acc[ai][1][m][1];
;                 const f32x2 ha = swiglu_pk((f32x2){g0[0], g0[1]}, (f32x2){u0[0], u0[1]}), hb = swiglu_pk((f32x2){g0[2], g0[3]}, (f32x2){u0[2], u0[3]});
;                 const f32x2 hc = swiglu_pk((f32x2){g1[0], g1[1]}, (f32x2){u1[0], u1[1]}), hd = swiglu_pk((f32x2){g1[2], g1[3]}, (f32x2){u1[2], u1[3]});
;                 u32x4 w; w.x = pk2(ha.x, ha.y); w.y = pk2(hb.x, hb.y); w.z = pk2(hc.x, hc.y); w.w = pk2(hd.x, hd.y);
;                 *(u32x4*)rowp = w;
;             }
	v_add_f32_e32 v83, 1.0, v83
	v_rcp_f32_e32 v82, v82
	v_rcp_f32_e32 v83, v83
	v_mul_f32_e32 v76, v76, v82
	v_mul_f32_e32 v77, v77, v83
	v_mul_f32_e32 v72, v76, v72
	v_mul_f32_e32 v73, v77, v73
	v_mul_f32_e32 v76, s30, v78
	v_mul_f32_e32 v77, s30, v79
	v_exp_f32_e32 v76, v76
	v_exp_f32_e32 v77, v77
	v_add_f32_e32 v76, 1.0, v76
	v_add_f32_e32 v77, 1.0, v77
	v_rcp_f32_e32 v76, v76
	v_rcp_f32_e32 v77, v77
	v_mul_f32_e32 v76, v78, v76
	v_mul_f32_e32 v77, v79, v77
	v_mul_f32_e32 v74, v76, v74
	v_mul_f32_e32 v75, v77, v75
	v_mul_f32_e32 v76, s30, v68
	v_mul_f32_e32 v77, s30, v69
	v_exp_f32_e32 v76, v76
	v_exp_f32_e32 v77, v77
	v_add_f32_e32 v76, 1.0, v76
	v_add_f32_e32 v77, 1.0, v77
	v_rcp_f32_e32 v76, v76
	v_rcp_f32_e32 v77, v77
	v_mul_f32_e32 v68, v68, v76
	v_mul_f32_e32 v69, v69, v77
	v_mul_f32_e32 v68, v68, v64
	v_mul_f32_e32 v69, v69, v65
	v_mul_f32_e32 v64, s30, v70
	v_mul_f32_e32 v65, s30, v71
	v_exp_f32_e32 v64, v64
	v_exp_f32_e32 v65, v65
	v_add_f32_e32 v64, 1.0, v64
	v_add_f32_e32 v65, 1.0, v65
	v_rcp_f32_e32 v64, v64
	v_rcp_f32_e32 v65, v65
	v_mul_f32_e32 v64, v70, v64
	v_mul_f32_e32 v65, v71, v65
	v_mul_f32_e32 v70, v64, v66
	v_mul_f32_e32 v71, v65, v67
	v_cvt_pk_bf16_f32 v64, v72, v73
	v_cvt_pk_bf16_f32 v65, v74, v75
	v_cvt_pk_bf16_f32 v66, v68, v69
	v_cvt_pk_bf16_f32 v67, v70, v71
	global_store_dwordx4 v[80:81], v[64:67], off sc1
	s_nop 1
	v_mul_f32_e32 v66, s30, v60
	v_mul_f32_e32 v67, s30, v61
	v_add_u32_e32 v64, 0x80, v148
	v_exp_f32_e32 v66, v66
	v_exp_f32_e32 v67, v67
	v_mad_i64_i32 v[64:65], s[20:21], v64, s15, v[140:141]
	v_lshl_add_u64 v[64:65], v[64:65], 0, v[142:143]
	v_add_f32_e32 v66, 1.0, v66
	v_add_f32_e32 v67, 1.0, v67
	v_rcp_f32_e32 v66, v66
	v_rcp_f32_e32 v67, v67
	v_mul_f32_e32 v60, v60, v66
	v_mul_f32_e32 v61, v61, v67
	v_mul_f32_e32 v56, v60, v56
	v_mul_f32_e32 v57, v61, v57
	v_mul_f32_e32 v60, s30, v62
	v_mul_f32_e32 v61, s30, v63
	v_exp_f32_e32 v60, v60
	v_exp_f32_e32 v61, v61
	v_add_f32_e32 v60, 1.0, v60
	v_add_f32_e32 v61, 1.0, v61
	v_rcp_f32_e32 v60, v60
	v_rcp_f32_e32 v61, v61
	v_mul_f32_e32 v60, v62, v60
	v_mul_f32_e32 v61, v63, v61
	v_mul_f32_e32 v58, v60, v58
	v_mul_f32_e32 v59, v61, v59
	v_mul_f32_e32 v60, s30, v52
	v_mul_f32_e32 v61, s30, v53
	v_exp_f32_e32 v60, v60
	v_exp_f32_e32 v61, v61
	v_add_f32_e32 v60, 1.0, v60
	v_add_f32_e32 v61, 1.0, v61
	v_rcp_f32_e32 v60, v60
	v_rcp_f32_e32 v61, v61
	v_mul_f32_e32 v52, v52, v60
	v_mul_f32_e32 v53, v53, v61
	v_mul_f32_e32 v52, v52, v48
	v_mul_f32_e32 v53, v53, v49
	v_mul_f32_e32 v48, s30, v54
	v_mul_f32_e32 v49, s30, v55
	v_exp_f32_e32 v48, v48
	v_exp_f32_e32 v49, v49
	v_add_f32_e32 v48, 1.0, v48
	v_add_f32_e32 v49, 1.0, v49
	v_rcp_f32_e32 v48, v48
	v_rcp_f32_e32 v49, v49
	v_mul_f32_e32 v48, v54, v48
	v_mul_f32_e32 v49, v55, v49
	v_mul_f32_e32 v54, v48, v50
	v_mul_f32_e32 v55, v49, v51
	v_cvt_pk_bf16_f32 v48, v56, v57
	v_cvt_pk_bf16_f32 v49, v58, v59
	v_cvt_pk_bf16_f32 v50, v52, v53
	v_cvt_pk_bf16_f32 v51, v54, v55
	global_store_dwordx4 v[64:65], v[48:51], off sc1
	s_nop 1
	v_mul_f32_e32 v50, s30, v44
	v_mul_f32_e32 v51, s30, v45
	v_add_u32_e32 v48, 0x90, v148
	v_exp_f32_e32 v50, v50
	v_exp_f32_e32 v51, v51
	v_mad_i64_i32 v[48:49], s[20:21], v48, s15, v[140:141]
	v_lshl_add_u64 v[48:49], v[48:49], 0, v[142:143]
	v_add_f32_e32 v50, 1.0, v50
	v_add_f32_e32 v51, 1.0, v51
	v_rcp_f32_e32 v50, v50
	v_rcp_f32_e32 v51, v51
	v_mul_f32_e32 v44, v44, v50
	v_mul_f32_e32 v45, v45, v51
	v_mul_f32_e32 v40, v44, v40
	v_mul_f32_e32 v41, v45, v41
	v_mul_f32_e32 v44, s30, v46
	v_mul_f32_e32 v45, s30, v47
	v_exp_f32_e32 v44, v44
	v_exp_f32_e32 v45, v45
	v_add_f32_e32 v44, 1.0, v44
	v_add_f32_e32 v45, 1.0, v45
	v_rcp_f32_e32 v44, v44
	v_rcp_f32_e32 v45, v45
	v_mul_f32_e32 v44, v46, v44
	v_mul_f32_e32 v45, v47, v45
	v_mul_f32_e32 v42, v44, v42
	v_mul_f32_e32 v43, v45, v43
	v_mul_f32_e32 v44, s30, v36
	v_mul_f32_e32 v45, s30, v37
	v_exp_f32_e32 v44, v44
	v_exp_f32_e32 v45, v45
	v_add_f32_e32 v44, 1.0, v44
	v_add_f32_e32 v45, 1.0, v45
	v_rcp_f32_e32 v44, v44
	v_rcp_f32_e32 v45, v45
; DI unsigned pk2(float lo, float hi) { f32x2 v = {lo, hi}; return __builtin_bit_cast(unsigned, __builtin_convertvector(v, bf2_t)); }
; DI f32x2 swiglu_pk(f32x2 g, f32x2 u) {
;     const f32x2 t = g * (-1.44269504089f);
;     f32x2 e; e.x = __builtin_amdgcn_exp2f(t.x); e.y = __builtin_amdgcn_exp2f(t.y);
;     const f32x2 d = e + 1.0f;
;     f32x2 r; r.x = __builtin_amdgcn_rcpf(d.x); r.y = __builtin_amdgcn_rcpf(d.y);
;     return (g * r) * u;
; }
;     DI void operator()(const f32x4 (&acc)[2][2][4][2], const Unit& u, int wr, int wc, int fr, int fq) const {
;         const int row0 = u.pm * BM + wr * 64 + fr, col0 = u.pn * HALF + wc * 32 + 8 * fq;
; #pragma unroll
;         for (int ai = 0; ai < 2; ++ai)
; #pragma unroll
;             for (int m = 0; m < 4; ++m) {
;                 bf16_t* rowp = H + (size_t)(row0 + ai * HALF + m * 16) * ldh + col0;
;                 const f32x4 g0 = acc[ai][0][m][0], g1 = acc[ai][0][m][1], u0 = acc[ai][1][m][0], u1 = acc[ai][1][m][1];
;                 const f32x2 ha = swiglu_pk((f32x2){g0[0], g0[1]}, (f32x2){u0[0], u0[1]}), hb = swiglu_pk((f32x2){g0[2], g0[3]}, (f32x2){u0[2], u0[3]});
;                 const f32x2 hc = swiglu_pk((f32x2){g1[0], g1[1]}, (f32x2){u1[0], u1[1]}), hd = swiglu_pk((f32x2){g1[2], g1[3]}, (f32x2){u1[2], u1[3]});
;                 u32x4 w; w.x = pk2(ha.x, ha.y); w.y = pk2(hb.x, hb.y); w.z = pk2(hc.x, hc.y); w.w = pk2(hd.x, hd.y);
;                 *(u32x4*)rowp = w;
;             }
	v_mul_f32_e32 v36, v36, v44
	v_mul_f32_e32 v37, v37, v45
	v_mul_f32_e32 v36, v36, v32
	v_mul_f32_e32 v37, v37, v33
	v_mul_f32_e32 v32, s30, v38
	v_mul_f32_e32 v33, s30, v39
	v_exp_f32_e32 v32, v32
	v_exp_f32_e32 v33, v33
	v_add_f32_e32 v32, 1.0, v32
	v_add_f32_e32 v33, 1.0, v33
	v_rcp_f32_e32 v32, v32
	v_rcp_f32_e32 v33, v33
	v_mul_f32_e32 v32, v38, v32
	v_mul_f32_e32 v33, v39, v33
	v_mul_f32_e32 v38, v32, v34
	v_mul_f32_e32 v39, v33, v35
	v_cvt_pk_bf16_f32 v32, v40, v41
	v_cvt_pk_bf16_f32 v33, v42, v43
	v_cvt_pk_bf16_f32 v34, v36, v37
	v_cvt_pk_bf16_f32 v35, v38, v39
	global_store_dwordx4 v[48:49], v[32:35], off sc1
	s_nop 1
	v_mul_f32_e32 v34, s30, v28
	v_mul_f32_e32 v35, s30, v29
	v_add_u32_e32 v32, 0xa0, v148
	v_exp_f32_e32 v34, v34
	v_exp_f32_e32 v35, v35
	v_mad_i64_i32 v[32:33], s[20:21], v32, s15, v[140:141]
	v_lshl_add_u64 v[32:33], v[32:33], 0, v[142:143]
	v_add_f32_e32 v34, 1.0, v34
	v_add_f32_e32 v35, 1.0, v35
	v_rcp_f32_e32 v34, v34
	v_rcp_f32_e32 v35, v35
	v_mul_f32_e32 v28, v28, v34
	v_mul_f32_e32 v29, v29, v35
	v_mul_f32_e32 v24, v28, v24
	v_mul_f32_e32 v25, v29, v25
	v_mul_f32_e32 v28, s30, v30
	v_mul_f32_e32 v29, s30, v31
	v_exp_f32_e32 v28, v28
	v_exp_f32_e32 v29, v29
	v_add_f32_e32 v28, 1.0, v28
	v_add_f32_e32 v29, 1.0, v29
	v_rcp_f32_e32 v28, v28
	v_rcp_f32_e32 v29, v29
	v_mul_f32_e32 v28, v30, v28
	v_mul_f32_e32 v29, v31, v29
	v_mul_f32_e32 v26, v28, v26
	v_mul_f32_e32 v27, v29, v27
	v_mul_f32_e32 v28, s30, v20
	v_mul_f32_e32 v29, s30, v21
	v_exp_f32_e32 v28, v28
	v_exp_f32_e32 v29, v29
	v_add_f32_e32 v28, 1.0, v28
	v_add_f32_e32 v29, 1.0, v29
	v_rcp_f32_e32 v28, v28
	v_rcp_f32_e32 v29, v29
	v_mul_f32_e32 v20, v20, v28
	v_mul_f32_e32 v21, v21, v29
	v_mul_f32_e32 v20, v20, v16
	v_mul_f32_e32 v21, v21, v17
	v_mul_f32_e32 v16, s30, v22
	v_mul_f32_e32 v17, s30, v23
	v_exp_f32_e32 v16, v16
	v_exp_f32_e32 v17, v17
	v_add_f32_e32 v16, 1.0, v16
	v_add_f32_e32 v17, 1.0, v17
	v_rcp_f32_e32 v16, v16
	v_rcp_f32_e32 v17, v17
	v_mul_f32_e32 v16, v22, v16
	v_mul_f32_e32 v17, v23, v17
	v_mul_f32_e32 v22, v16, v18
	v_mul_f32_e32 v23, v17, v19
	v_cvt_pk_bf16_f32 v16, v24, v25
	v_cvt_pk_bf16_f32 v17, v26, v27
	v_cvt_pk_bf16_f32 v18, v20, v21
	v_cvt_pk_bf16_f32 v19, v22, v23
	global_store_dwordx4 v[32:33], v[16:19], off sc1
	s_nop 1
	v_mul_f32_e32 v18, s30, v12
	v_mul_f32_e32 v19, s30, v13
	v_add_u32_e32 v16, 0xb0, v148
	v_exp_f32_e32 v18, v18
	v_exp_f32_e32 v19, v19
	v_mad_i64_i32 v[16:17], s[20:21], v16, s15, v[140:141]
	v_lshl_add_u64 v[16:17], v[16:17], 0, v[142:143]
	v_add_f32_e32 v18, 1.0, v18
	v_add_f32_e32 v19, 1.0, v19
	s_mov_b64 s[20:21], -1
	v_rcp_f32_e32 v18, v18
	v_rcp_f32_e32 v19, v19
	v_mul_f32_e32 v12, v12, v18
	v_mul_f32_e32 v13, v13, v19
	v_mul_f32_e32 v8, v12, v8
	v_mul_f32_e32 v9, v13, v9
	v_mul_f32_e32 v12, s30, v14
	v_mul_f32_e32 v13, s30, v15
	v_exp_f32_e32 v12, v12
	v_exp_f32_e32 v13, v13
	v_add_f32_e32 v12, 1.0, v12
	v_add_f32_e32 v13, 1.0, v13
	v_rcp_f32_e32 v12, v12
	v_rcp_f32_e32 v13, v13
	v_mul_f32_e32 v12, v14, v12
	v_mul_f32_e32 v13, v15, v13
	v_mul_f32_e32 v10, v12, v10
	v_mul_f32_e32 v11, v13, v11
	v_mul_f32_e32 v12, s30, v4
	v_mul_f32_e32 v13, s30, v5
	v_exp_f32_e32 v12, v12
	v_exp_f32_e32 v13, v13
	v_add_f32_e32 v12, 1.0, v12
	v_add_f32_e32 v13, 1.0, v13
	v_rcp_f32_e32 v12, v12
	v_rcp_f32_e32 v13, v13
	v_mul_f32_e32 v4, v4, v12
	v_mul_f32_e32 v5, v5, v13
	v_mul_f32_e32 v4, v4, v0
	v_mul_f32_e32 v5, v5, v1
	v_mul_f32_e32 v0, s30, v6
	v_mul_f32_e32 v1, s30, v7
	v_exp_f32_e32 v0, v0
	v_exp_f32_e32 v1, v1
	v_add_f32_e32 v0, 1.0, v0
	v_add_f32_e32 v1, 1.0, v1
	v_rcp_f32_e32 v0, v0
	v_rcp_f32_e32 v1, v1
	v_mul_f32_e32 v0, v6, v0
	v_mul_f32_e32 v1, v7, v1
	v_mul_f32_e32 v6, v0, v2
	v_mul_f32_e32 v7, v1, v3
	v_cvt_pk_bf16_f32 v0, v8, v9
	v_cvt_pk_bf16_f32 v1, v10, v11
	v_cvt_pk_bf16_f32 v2, v4, v5
	v_cvt_pk_bf16_f32 v3, v6, v7
	global_store_dwordx4 v[16:17], v[0:3], off sc1
	s_cbranch_vccnz .LBB0_236
	s_andn2_b64 vcc, exec, s[22:23]
	s_cbranch_vccnz .LBB0_235
	s_barrier
	s_branch .LBB0_235
